# GEMM K-loops: the two k-steps of each accumulator issued back to back inside every 16-MFMA cluster (on top of v22)
# speedup vs baseline: 1.0058x; 1.0052x over previous
; #define PG8_STAGE(bufoff, gbase, voff) do { _Pragma("unroll") for (int _i = 0; _i < 2; ++_i) \
;         __builtin_amdgcn_global_load_lds((const unsigned*)((const char*)(gbase) + (voff)[_i]), (PG8_LAS unsigned*)(lds + (bufoff) + ldsw + _i * 8192), 16, 0, 0); } while (0)
; #define PG8_LDA(dst, b, h) do { _Pragma("unroll") for (int m = 0; m < 4; ++m) _Pragma("unroll") for (int k = 0; k < 2; ++k) dst[m][k] = *(const PG8_LAS bf16x8*)(lds + PG8_SA(b, h) + aoff + m * 2048 + k * 1024); } while (0)
; #define PG8_LDB(dst, b, h) do { _Pragma("unroll") for (int n = 0; n < 2; ++n) _Pragma("unroll") for (int k = 0; k < 2; ++k) dst[n][k] = *(const PG8_LAS bf16x8*)(lds + PG8_SB(b, h) + boff + n * 2048 + k * 1024); } while (0)
; #define PG8_MMA(ai, bj, At, Bt) do { __builtin_amdgcn_s_setprio(1); _Pragma("unroll") for (int m = 0; m < 4; ++m) _Pragma("unroll") for (int n = 0; n < 2; ++n) _Pragma("unroll") for (int k = 0; k < 2; ++k) \
;         acc[ai][bj][m][n] = __builtin_amdgcn_mfma_f32_16x16x32_bf16(Bt[n][k], At[m][k], acc[ai][bj][m][n], 0, 0, 0); __builtin_amdgcn_s_setprio(0); } while (0)
; #define PG8_WAIT_V(n) asm volatile("s_waitcnt vmcnt(" #n ")" ::: "memory")
; #define PG8_BAR __builtin_amdgcn_s_barrier()
; template <class Epi, class Sched, bool ALIGN_EPI = false, bool SP2 = false>
; __device__ __forceinline__ void gemm_phase(PG8_LAS unsigned char* lds, const Gemm g, const Sched& S, const Epi& E) {
;     ...
;         for (int t = 0; t < nt; t += 2) {
;             const bool last = (t == nt - 2);
;             const char* a1 = cA + (size_t)(t + 1) * kstep;
;             const char* a2 = last ? nA : cA + (size_t)(t + 2) * kstep; const char* b2 = last ? nB : cB + (size_t)(t + 2) * kstep;
;             const char* a3 = a2 + kstep; const char* b3 = b2 + kstep;
;             if (last && has_next) S.a_ready(nxt);
;             if constexpr (SP2) {
;             PG8_LDB(B0, 0, 0); PG8_LDB(B1, 0, 1); PG8_SCHED; PG8_LDA(At, 0, 0); PG8_STAGE(PG8_SA(1, 1), a1 + hstep, voffA);
;             PG8_WAIT_V(8); PG8_WAIT_L(0); PG8_BAR; PG8_MMA(0, 0, At, B0); PG8_MMA(0, 1, At, B1); PG8_BAR; PG8_SCHED;
;             PG8_LDA(At, 0, 1); PG8_STAGE(PG8_SB(0, 0), b2, voffB); PG8_STAGE(PG8_SB(0, 1), b2 + hstep, voffB); PG8_STAGE(PG8_SA(0, 0), a2, voffA);
;             PG8_WAIT_V(8); PG8_WAIT_L(0); PG8_BAR; PG8_MMA(1, 0, At, B0); PG8_MMA(1, 1, At, B1); PG8_BAR; PG8_SCHED;
.LBB0_85:
	s_add_u32 s40, s38, 0xfff80080
	s_addc_u32 s41, s39, -1
	s_add_i32 s45, 0, 0x10000
	s_cmp_eq_u32 s44, 28
	s_cselect_b32 s43, s5, s41
	s_cselect_b32 s42, s12, s40
	s_cselect_b32 s41, s23, s37
	s_cselect_b32 s40, s25, s31
	s_add_i32 s48, 0, 0x14000
	v_add_u32_e32 v140, s45, v184
	v_add_u32_e32 v154, s48, v184
	ds_read_b128 v[128:131], v140
	ds_read_b128 v[132:135], v140 offset:1024
	ds_read_b128 v[136:139], v140 offset:2048
	ds_read_b128 v[140:143], v140 offset:3072
	ds_read_b128 v[164:167], v154
	ds_read_b128 v[168:171], v154 offset:1024
	ds_read_b128 v[172:175], v154 offset:2048
	ds_read_b128 v[186:189], v154 offset:3072
	v_lshl_add_u64 v[222:223], s[38:39], 0, v[158:159]
	s_add_i32 m0, s58, 0xc000
	ds_read_b128 v[190:193], v185
	ds_read_b128 v[194:197], v185 offset:1024
	ds_read_b128 v[198:201], v185 offset:2048
	ds_read_b128 v[202:205], v185 offset:3072
	ds_read_b128 v[206:209], v185 offset:4096
	ds_read_b128 v[210:213], v185 offset:5120
	ds_read_b128 v[214:217], v185 offset:6144
	ds_read_b128 v[218:221], v185 offset:7168
	global_load_lds_dwordx4 v[222:223], off
	v_lshl_add_u64 v[222:223], s[38:39], 0, v[160:161]
	s_add_i32 m0, s58, 0xe000
	s_nop 0
	global_load_lds_dwordx4 v[222:223], off
	s_waitcnt vmcnt(8)
	s_waitcnt lgkmcnt(0)
	s_barrier
	s_setprio 1
	s_waitcnt lgkmcnt(0)
	v_mfma_f32_16x16x32_bf16 v[124:127], v[128:131], v[190:193], v[124:127]
	v_mfma_f32_16x16x32_bf16 v[124:127], v[132:135], v[194:197], v[124:127]
	v_mfma_f32_16x16x32_bf16 v[116:119], v[136:139], v[190:193], v[116:119]
	v_mfma_f32_16x16x32_bf16 v[116:119], v[140:143], v[194:197], v[116:119]
	v_mfma_f32_16x16x32_bf16 v[108:111], v[128:131], v[198:201], v[108:111]
	v_mfma_f32_16x16x32_bf16 v[108:111], v[132:135], v[202:205], v[108:111]
	v_mfma_f32_16x16x32_bf16 v[104:107], v[136:139], v[198:201], v[104:107]
	v_mfma_f32_16x16x32_bf16 v[104:107], v[140:143], v[202:205], v[104:107]
	v_mfma_f32_16x16x32_bf16 v[92:95], v[128:131], v[206:209], v[92:95]
	v_mfma_f32_16x16x32_bf16 v[92:95], v[132:135], v[210:213], v[92:95]
	v_mfma_f32_16x16x32_bf16 v[88:91], v[136:139], v[206:209], v[88:91]
	v_mfma_f32_16x16x32_bf16 v[88:91], v[140:143], v[210:213], v[88:91]
	v_mfma_f32_16x16x32_bf16 v[76:79], v[128:131], v[214:217], v[76:79]
	v_mfma_f32_16x16x32_bf16 v[76:79], v[132:135], v[218:221], v[76:79]
	v_mfma_f32_16x16x32_bf16 v[72:75], v[136:139], v[214:217], v[72:75]
	v_mfma_f32_16x16x32_bf16 v[72:75], v[140:143], v[218:221], v[72:75]
	s_setprio 0
	s_setprio 1
	v_mfma_f32_16x16x32_bf16 v[120:123], v[164:167], v[190:193], v[120:123]
	v_mfma_f32_16x16x32_bf16 v[120:123], v[168:171], v[194:197], v[120:123]
	v_mfma_f32_16x16x32_bf16 v[112:115], v[172:175], v[190:193], v[112:115]
	v_mfma_f32_16x16x32_bf16 v[112:115], v[186:189], v[194:197], v[112:115]
	v_mfma_f32_16x16x32_bf16 v[100:103], v[164:167], v[198:201], v[100:103]
	v_mfma_f32_16x16x32_bf16 v[100:103], v[168:171], v[202:205], v[100:103]
	v_mfma_f32_16x16x32_bf16 v[96:99], v[172:175], v[198:201], v[96:99]
	v_mfma_f32_16x16x32_bf16 v[96:99], v[186:189], v[202:205], v[96:99]
	v_mfma_f32_16x16x32_bf16 v[84:87], v[164:167], v[206:209], v[84:87]
	v_mfma_f32_16x16x32_bf16 v[84:87], v[168:171], v[210:213], v[84:87]
	v_mfma_f32_16x16x32_bf16 v[80:83], v[172:175], v[206:209], v[80:83]
	v_mfma_f32_16x16x32_bf16 v[80:83], v[186:189], v[210:213], v[80:83]
	v_mfma_f32_16x16x32_bf16 v[68:71], v[164:167], v[214:217], v[68:71]
	v_mfma_f32_16x16x32_bf16 v[68:71], v[168:171], v[218:221], v[68:71]
	v_mfma_f32_16x16x32_bf16 v[64:67], v[172:175], v[214:217], v[64:67]
	v_mfma_f32_16x16x32_bf16 v[64:67], v[186:189], v[218:221], v[64:67]
	s_setprio 0
	s_barrier
	s_add_i32 s45, s45, s57
	v_lshl_add_u64 v[222:223], s[40:41], 0, v[148:149]
	s_mov_b32 m0, s45
	ds_read_b128 v[190:193], v185 offset:16384
	ds_read_b128 v[194:197], v185 offset:17408
	ds_read_b128 v[198:201], v185 offset:18432
	ds_read_b128 v[202:205], v185 offset:19456
	ds_read_b128 v[206:209], v185 offset:20480
	ds_read_b128 v[210:213], v185 offset:21504
	ds_read_b128 v[214:217], v185 offset:22528
	ds_read_b128 v[218:221], v185 offset:23552
	global_load_lds_dwordx4 v[222:223], off
	s_add_i32 m0, s45, 0x2000
	s_add_u32 s46, s40, 0x80000
	v_lshl_add_u64 v[224:225], s[40:41], 0, v[152:153]
	s_addc_u32 s47, s41, 0
	s_add_i32 s45, s48, s57
	global_load_lds_dwordx4 v[224:225], off
	v_lshl_add_u64 v[226:227], s[46:47], 0, v[148:149]
	s_mov_b32 m0, s45
	v_lshl_add_u64 v[232:233], s[42:43], 0, v[150:151]
	global_load_lds_dwordx4 v[226:227], off
	v_lshl_add_u64 v[226:227], s[46:47], 0, v[152:153]
	s_add_i32 m0, s45, 0x2000
	s_nop 0
	global_load_lds_dwordx4 v[226:227], off
	v_lshl_add_u64 v[226:227], s[42:43], 0, v[146:147]
	s_mov_b32 m0, s58
	s_nop 0
	global_load_lds_dwordx4 v[226:227], off
	s_mov_b32 m0, s59
	s_nop 0
	global_load_lds_dwordx4 v[232:233], off
	s_waitcnt vmcnt(8)
	s_waitcnt lgkmcnt(0)
	s_barrier
; #define PG8_STAGE(bufoff, gbase, voff) do { _Pragma("unroll") for (int _i = 0; _i < 2; ++_i) \
;         __builtin_amdgcn_global_load_lds((const unsigned*)((const char*)(gbase) + (voff)[_i]), (PG8_LAS unsigned*)(lds + (bufoff) + ldsw + _i * 8192), 16, 0, 0); } while (0)
; #define PG8_LDA(dst, b, h) do { _Pragma("unroll") for (int m = 0; m < 4; ++m) _Pragma("unroll") for (int k = 0; k < 2; ++k) dst[m][k] = *(const PG8_LAS bf16x8*)(lds + PG8_SA(b, h) + aoff + m * 2048 + k * 1024); } while (0)
; #define PG8_LDB(dst, b, h) do { _Pragma("unroll") for (int n = 0; n < 2; ++n) _Pragma("unroll") for (int k = 0; k < 2; ++k) dst[n][k] = *(const PG8_LAS bf16x8*)(lds + PG8_SB(b, h) + boff + n * 2048 + k * 1024); } while (0)
; #define PG8_MMA(ai, bj, At, Bt) do { __builtin_amdgcn_s_setprio(1); _Pragma("unroll") for (int m = 0; m < 4; ++m) _Pragma("unroll") for (int n = 0; n < 2; ++n) _Pragma("unroll") for (int k = 0; k < 2; ++k) \
;         acc[ai][bj][m][n] = __builtin_amdgcn_mfma_f32_16x16x32_bf16(Bt[n][k], At[m][k], acc[ai][bj][m][n], 0, 0, 0); __builtin_amdgcn_s_setprio(0); } while (0)
; #define PG8_WAIT_V(n) asm volatile("s_waitcnt vmcnt(" #n ")" ::: "memory")
; #define PG8_WAIT_L(n) asm volatile("s_waitcnt lgkmcnt(" #n ")" ::: "memory")
; #define PG8_BAR __builtin_amdgcn_s_barrier()
; #define PG8_SCHED __builtin_amdgcn_sched_barrier(0)
; template <class Epi, class Sched, bool ALIGN_EPI = false, bool SP2 = false>
; __device__ __forceinline__ void gemm_phase(PG8_LAS unsigned char* lds, const Gemm g, const Sched& S, const Epi& E) {
;     ...
;             PG8_WAIT_V(8); PG8_WAIT_L(0); PG8_BAR; PG8_MMA(1, 0, At, B0); PG8_MMA(1, 1, At, B1); PG8_BAR; PG8_SCHED;
;             PG8_LDB(B0, 1, 0); PG8_LDB(B1, 1, 1); PG8_SCHED; PG8_LDA(At, 1, 0); PG8_STAGE(PG8_SA(0, 1), a2 + hstep, voffA);
;             PG8_WAIT_V(8); PG8_WAIT_L(0); PG8_BAR; PG8_MMA(0, 0, At, B0); PG8_MMA(0, 1, At, B1); PG8_BAR; PG8_SCHED;
;             PG8_LDA(At, 1, 1); PG8_STAGE(PG8_SB(1, 0), b3, voffB); PG8_STAGE(PG8_SB(1, 1), b3 + hstep, voffB); PG8_STAGE(PG8_SA(1, 0), a3, voffA);
;             PG8_WAIT_V(8); PG8_WAIT_L(0); PG8_BAR; PG8_MMA(1, 0, At, B0); PG8_MMA(1, 1, At, B1); PG8_BAR; PG8_SCHED;
	s_setprio 1
	s_waitcnt lgkmcnt(0)
	v_mfma_f32_16x16x32_bf16 v[60:63], v[128:131], v[190:193], v[60:63]
	v_mfma_f32_16x16x32_bf16 v[60:63], v[132:135], v[194:197], v[60:63]
	v_mfma_f32_16x16x32_bf16 v[56:59], v[136:139], v[190:193], v[56:59]
	v_mfma_f32_16x16x32_bf16 v[56:59], v[140:143], v[194:197], v[56:59]
	v_mfma_f32_16x16x32_bf16 v[44:47], v[128:131], v[198:201], v[44:47]
	v_mfma_f32_16x16x32_bf16 v[44:47], v[132:135], v[202:205], v[44:47]
	v_mfma_f32_16x16x32_bf16 v[40:43], v[136:139], v[198:201], v[40:43]
	v_mfma_f32_16x16x32_bf16 v[40:43], v[140:143], v[202:205], v[40:43]
	v_mfma_f32_16x16x32_bf16 v[28:31], v[128:131], v[206:209], v[28:31]
	v_mfma_f32_16x16x32_bf16 v[28:31], v[132:135], v[210:213], v[28:31]
	v_mfma_f32_16x16x32_bf16 v[24:27], v[136:139], v[206:209], v[24:27]
	v_mfma_f32_16x16x32_bf16 v[24:27], v[140:143], v[210:213], v[24:27]
	v_mfma_f32_16x16x32_bf16 v[12:15], v[128:131], v[214:217], v[12:15]
	v_mfma_f32_16x16x32_bf16 v[12:15], v[132:135], v[218:221], v[12:15]
	v_mfma_f32_16x16x32_bf16 v[8:11], v[136:139], v[214:217], v[8:11]
	v_mfma_f32_16x16x32_bf16 v[8:11], v[140:143], v[218:221], v[8:11]
	s_setprio 0
	s_setprio 1
	v_mfma_f32_16x16x32_bf16 v[52:55], v[164:167], v[190:193], v[52:55]
	v_mfma_f32_16x16x32_bf16 v[52:55], v[168:171], v[194:197], v[52:55]
	v_mfma_f32_16x16x32_bf16 v[48:51], v[172:175], v[190:193], v[48:51]
	v_mfma_f32_16x16x32_bf16 v[48:51], v[186:189], v[194:197], v[48:51]
	v_mfma_f32_16x16x32_bf16 v[36:39], v[164:167], v[198:201], v[36:39]
	v_mfma_f32_16x16x32_bf16 v[36:39], v[168:171], v[202:205], v[36:39]
	v_mfma_f32_16x16x32_bf16 v[32:35], v[172:175], v[198:201], v[32:35]
	v_mfma_f32_16x16x32_bf16 v[32:35], v[186:189], v[202:205], v[32:35]
	v_mfma_f32_16x16x32_bf16 v[20:23], v[164:167], v[206:209], v[20:23]
	v_mfma_f32_16x16x32_bf16 v[20:23], v[168:171], v[210:213], v[20:23]
	v_mfma_f32_16x16x32_bf16 v[16:19], v[172:175], v[206:209], v[16:19]
	v_mfma_f32_16x16x32_bf16 v[16:19], v[186:189], v[210:213], v[16:19]
	v_mfma_f32_16x16x32_bf16 v[4:7], v[164:167], v[214:217], v[4:7]
	v_mfma_f32_16x16x32_bf16 v[4:7], v[168:171], v[218:221], v[4:7]
	v_mfma_f32_16x16x32_bf16 v[0:3], v[172:175], v[214:217], v[0:3]
	v_mfma_f32_16x16x32_bf16 v[0:3], v[186:189], v[218:221], v[0:3]
	s_setprio 0
	s_barrier
	s_add_i32 s45, 0, 0x18000
	s_add_i32 s46, 0, 0x1c000
	v_add_u32_e32 v140, s45, v184
	v_add_u32_e32 v154, s46, v184
	ds_read_b128 v[128:131], v140
	ds_read_b128 v[132:135], v140 offset:1024
	ds_read_b128 v[136:139], v140 offset:2048
	ds_read_b128 v[140:143], v140 offset:3072
	ds_read_b128 v[164:167], v154
	ds_read_b128 v[168:171], v154 offset:1024
	ds_read_b128 v[172:175], v154 offset:2048
	ds_read_b128 v[186:189], v154 offset:3072
	s_add_u32 s42, s42, 0x80000
	s_addc_u32 s43, s43, 0
	s_mov_b32 m0, s60
	v_lshl_add_u64 v[234:235], s[42:43], 0, v[146:147]
	ds_read_b128 v[190:193], v185 offset:32768
	ds_read_b128 v[194:197], v185 offset:33792
	ds_read_b128 v[198:201], v185 offset:34816
	ds_read_b128 v[202:205], v185 offset:35840
	ds_read_b128 v[206:209], v185 offset:36864
	ds_read_b128 v[210:213], v185 offset:37888
	ds_read_b128 v[214:217], v185 offset:38912
	ds_read_b128 v[218:221], v185 offset:39936
	global_load_lds_dwordx4 v[234:235], off
	v_lshl_add_u64 v[234:235], s[42:43], 0, v[150:151]
	s_mov_b32 m0, s61
	s_nop 0
	global_load_lds_dwordx4 v[234:235], off
	s_waitcnt vmcnt(8)
	s_waitcnt lgkmcnt(0)
	s_barrier
	s_setprio 1
	s_waitcnt lgkmcnt(0)
	v_mfma_f32_16x16x32_bf16 v[124:127], v[128:131], v[190:193], v[124:127]
	v_mfma_f32_16x16x32_bf16 v[124:127], v[132:135], v[194:197], v[124:127]
	v_mfma_f32_16x16x32_bf16 v[116:119], v[136:139], v[190:193], v[116:119]
	v_mfma_f32_16x16x32_bf16 v[116:119], v[140:143], v[194:197], v[116:119]
	v_mfma_f32_16x16x32_bf16 v[108:111], v[128:131], v[198:201], v[108:111]
	v_mfma_f32_16x16x32_bf16 v[108:111], v[132:135], v[202:205], v[108:111]
	v_mfma_f32_16x16x32_bf16 v[104:107], v[136:139], v[198:201], v[104:107]
	v_mfma_f32_16x16x32_bf16 v[104:107], v[140:143], v[202:205], v[104:107]
	v_mfma_f32_16x16x32_bf16 v[92:95], v[128:131], v[206:209], v[92:95]
	v_mfma_f32_16x16x32_bf16 v[92:95], v[132:135], v[210:213], v[92:95]
	v_mfma_f32_16x16x32_bf16 v[88:91], v[136:139], v[206:209], v[88:91]
	v_mfma_f32_16x16x32_bf16 v[88:91], v[140:143], v[210:213], v[88:91]
	v_mfma_f32_16x16x32_bf16 v[76:79], v[128:131], v[214:217], v[76:79]
	v_mfma_f32_16x16x32_bf16 v[76:79], v[132:135], v[218:221], v[76:79]
	v_mfma_f32_16x16x32_bf16 v[72:75], v[136:139], v[214:217], v[72:75]
	v_mfma_f32_16x16x32_bf16 v[72:75], v[140:143], v[218:221], v[72:75]
	s_setprio 0
	s_setprio 1
	v_mfma_f32_16x16x32_bf16 v[120:123], v[164:167], v[190:193], v[120:123]
	v_mfma_f32_16x16x32_bf16 v[120:123], v[168:171], v[194:197], v[120:123]
	v_mfma_f32_16x16x32_bf16 v[112:115], v[172:175], v[190:193], v[112:115]
	v_mfma_f32_16x16x32_bf16 v[112:115], v[186:189], v[194:197], v[112:115]
	v_mfma_f32_16x16x32_bf16 v[100:103], v[164:167], v[198:201], v[100:103]
	v_mfma_f32_16x16x32_bf16 v[100:103], v[168:171], v[202:205], v[100:103]
	v_mfma_f32_16x16x32_bf16 v[96:99], v[172:175], v[198:201], v[96:99]
	v_mfma_f32_16x16x32_bf16 v[96:99], v[186:189], v[202:205], v[96:99]
	v_mfma_f32_16x16x32_bf16 v[84:87], v[164:167], v[206:209], v[84:87]
	v_mfma_f32_16x16x32_bf16 v[84:87], v[168:171], v[210:213], v[84:87]
	v_mfma_f32_16x16x32_bf16 v[80:83], v[172:175], v[206:209], v[80:83]
	v_mfma_f32_16x16x32_bf16 v[80:83], v[186:189], v[210:213], v[80:83]
	v_mfma_f32_16x16x32_bf16 v[68:71], v[164:167], v[214:217], v[68:71]
	v_mfma_f32_16x16x32_bf16 v[68:71], v[168:171], v[218:221], v[68:71]
	v_mfma_f32_16x16x32_bf16 v[64:67], v[172:175], v[214:217], v[64:67]
	v_mfma_f32_16x16x32_bf16 v[64:67], v[186:189], v[218:221], v[64:67]
	s_setprio 0
	s_barrier
; #define PG8_STAGE(bufoff, gbase, voff) do { _Pragma("unroll") for (int _i = 0; _i < 2; ++_i) \
;         __builtin_amdgcn_global_load_lds((const unsigned*)((const char*)(gbase) + (voff)[_i]), (PG8_LAS unsigned*)(lds + (bufoff) + ldsw + _i * 8192), 16, 0, 0); } while (0)
; #define PG8_LDA(dst, b, h) do { _Pragma("unroll") for (int m = 0; m < 4; ++m) _Pragma("unroll") for (int k = 0; k < 2; ++k) dst[m][k] = *(const PG8_LAS bf16x8*)(lds + PG8_SA(b, h) + aoff + m * 2048 + k * 1024); } while (0)
; #define PG8_MMA(ai, bj, At, Bt) do { __builtin_amdgcn_s_setprio(1); _Pragma("unroll") for (int m = 0; m < 4; ++m) _Pragma("unroll") for (int n = 0; n < 2; ++n) _Pragma("unroll") for (int k = 0; k < 2; ++k) \
;         acc[ai][bj][m][n] = __builtin_amdgcn_mfma_f32_16x16x32_bf16(Bt[n][k], At[m][k], acc[ai][bj][m][n], 0, 0, 0); __builtin_amdgcn_s_setprio(0); } while (0)
; #define PG8_WAIT_V(n) asm volatile("s_waitcnt vmcnt(" #n ")" ::: "memory")
; #define PG8_WAIT_L(n) asm volatile("s_waitcnt lgkmcnt(" #n ")" ::: "memory")
; #define PG8_BAR __builtin_amdgcn_s_barrier()
; #define PG8_SCHED __builtin_amdgcn_sched_barrier(0)
; template <class Epi, class Sched, bool ALIGN_EPI = false, bool SP2 = false>
; __device__ __forceinline__ void gemm_phase(PG8_LAS unsigned char* lds, const Gemm g, const Sched& S, const Epi& E) {
;     ...
;             PG8_LDA(At, 1, 1); PG8_STAGE(PG8_SB(1, 0), b3, voffB); PG8_STAGE(PG8_SB(1, 1), b3 + hstep, voffB); PG8_STAGE(PG8_SA(1, 0), a3, voffA);
;             PG8_WAIT_V(8); PG8_WAIT_L(0); PG8_BAR; PG8_MMA(1, 0, At, B0); PG8_MMA(1, 1, At, B1); PG8_BAR; PG8_SCHED;
	s_add_i32 s42, s45, s57
	v_lshl_add_u64 v[222:223], v[222:223], 0, s[14:15]
	s_mov_b32 m0, s42
	ds_read_b128 v[190:193], v185 offset:49152
	ds_read_b128 v[194:197], v185 offset:50176
	ds_read_b128 v[198:201], v185 offset:51200
	ds_read_b128 v[202:205], v185 offset:52224
	ds_read_b128 v[206:209], v185 offset:53248
	ds_read_b128 v[210:213], v185 offset:54272
	ds_read_b128 v[214:217], v185 offset:55296
	ds_read_b128 v[218:221], v185 offset:56320
	global_load_lds_dwordx4 v[222:223], off
	s_add_i32 m0, s42, 0x2000
	s_add_u32 s40, s40, 0x80080
	v_lshl_add_u64 v[222:223], v[224:225], 0, s[14:15]
	s_addc_u32 s41, s41, 0
	s_add_i32 s42, s46, s57
	global_load_lds_dwordx4 v[222:223], off
	v_lshl_add_u64 v[222:223], s[40:41], 0, v[148:149]
	s_mov_b32 m0, s42
	s_nop 0
	global_load_lds_dwordx4 v[222:223], off
	v_lshl_add_u64 v[222:223], s[40:41], 0, v[152:153]
	s_add_i32 m0, s42, 0x2000
	s_nop 0
	global_load_lds_dwordx4 v[222:223], off
	v_lshl_add_u64 v[222:223], v[226:227], 0, s[14:15]
	s_mov_b32 m0, s63
	s_nop 0
	global_load_lds_dwordx4 v[222:223], off
	v_lshl_add_u64 v[222:223], v[232:233], 0, s[14:15]
	s_mov_b32 m0, s64
	s_nop 0
	global_load_lds_dwordx4 v[222:223], off
	s_waitcnt vmcnt(8)
	s_waitcnt lgkmcnt(0)
	s_barrier
	s_setprio 1
	s_waitcnt lgkmcnt(0)
	v_mfma_f32_16x16x32_bf16 v[60:63], v[128:131], v[190:193], v[60:63]
	v_mfma_f32_16x16x32_bf16 v[60:63], v[132:135], v[194:197], v[60:63]
	v_mfma_f32_16x16x32_bf16 v[56:59], v[136:139], v[190:193], v[56:59]
	v_mfma_f32_16x16x32_bf16 v[56:59], v[140:143], v[194:197], v[56:59]
	v_mfma_f32_16x16x32_bf16 v[44:47], v[128:131], v[198:201], v[44:47]
	v_mfma_f32_16x16x32_bf16 v[44:47], v[132:135], v[202:205], v[44:47]
	v_mfma_f32_16x16x32_bf16 v[40:43], v[136:139], v[198:201], v[40:43]
	v_mfma_f32_16x16x32_bf16 v[40:43], v[140:143], v[202:205], v[40:43]
	v_mfma_f32_16x16x32_bf16 v[28:31], v[128:131], v[206:209], v[28:31]
	v_mfma_f32_16x16x32_bf16 v[28:31], v[132:135], v[210:213], v[28:31]
	v_mfma_f32_16x16x32_bf16 v[24:27], v[136:139], v[206:209], v[24:27]
	v_mfma_f32_16x16x32_bf16 v[24:27], v[140:143], v[210:213], v[24:27]
	v_mfma_f32_16x16x32_bf16 v[12:15], v[128:131], v[214:217], v[12:15]
	v_mfma_f32_16x16x32_bf16 v[12:15], v[132:135], v[218:221], v[12:15]
	v_mfma_f32_16x16x32_bf16 v[8:11], v[136:139], v[214:217], v[8:11]
	v_mfma_f32_16x16x32_bf16 v[8:11], v[140:143], v[218:221], v[8:11]
	s_setprio 0
	s_setprio 1
	v_mfma_f32_16x16x32_bf16 v[52:55], v[164:167], v[190:193], v[52:55]
	v_mfma_f32_16x16x32_bf16 v[52:55], v[168:171], v[194:197], v[52:55]
	v_mfma_f32_16x16x32_bf16 v[48:51], v[172:175], v[190:193], v[48:51]
	v_mfma_f32_16x16x32_bf16 v[48:51], v[186:189], v[194:197], v[48:51]
	v_mfma_f32_16x16x32_bf16 v[36:39], v[164:167], v[198:201], v[36:39]
	v_mfma_f32_16x16x32_bf16 v[36:39], v[168:171], v[202:205], v[36:39]
	v_mfma_f32_16x16x32_bf16 v[32:35], v[172:175], v[198:201], v[32:35]
	v_mfma_f32_16x16x32_bf16 v[32:35], v[186:189], v[202:205], v[32:35]
	v_mfma_f32_16x16x32_bf16 v[20:23], v[164:167], v[206:209], v[20:23]
	v_mfma_f32_16x16x32_bf16 v[20:23], v[168:171], v[210:213], v[20:23]
	v_mfma_f32_16x16x32_bf16 v[16:19], v[172:175], v[206:209], v[16:19]
	v_mfma_f32_16x16x32_bf16 v[16:19], v[186:189], v[210:213], v[16:19]
	v_mfma_f32_16x16x32_bf16 v[4:7], v[164:167], v[214:217], v[4:7]
	v_mfma_f32_16x16x32_bf16 v[4:7], v[168:171], v[218:221], v[4:7]
	v_mfma_f32_16x16x32_bf16 v[0:3], v[172:175], v[214:217], v[0:3]
	v_mfma_f32_16x16x32_bf16 v[0:3], v[186:189], v[218:221], v[0:3]
	s_setprio 0
	s_barrier
	s_add_i32 s44, s44, 2
	s_add_u32 s38, s38, 0x100
	s_addc_u32 s39, s39, 0
	s_add_u32 s31, s31, 0x100
	s_addc_u32 s37, s37, 0
	s_cmp_gt_u32 s44, 29
	s_cbranch_scc0 .LBB0_85
	s_and_b64 vcc, exec, s[20:21]
	s_cbranch_vccz .LBB0_88
	s_barrier

; #define PG8_STAGE(bufoff, gbase, voff) do { _Pragma("unroll") for (int _i = 0; _i < 2; ++_i) \
;         __builtin_amdgcn_global_load_lds((const unsigned*)((const char*)(gbase) + (voff)[_i]), (PG8_LAS unsigned*)(lds + (bufoff) + ldsw + _i * 8192), 16, 0, 0); } while (0)
; #define PG8_LDA(dst, b, h) do { _Pragma("unroll") for (int m = 0; m < 4; ++m) _Pragma("unroll") for (int k = 0; k < 2; ++k) dst[m][k] = *(const PG8_LAS bf16x8*)(lds + PG8_SA(b, h) + aoff + m * 2048 + k * 1024); } while (0)
; #define PG8_LDB(dst, b, h) do { _Pragma("unroll") for (int n = 0; n < 2; ++n) _Pragma("unroll") for (int k = 0; k < 2; ++k) dst[n][k] = *(const PG8_LAS bf16x8*)(lds + PG8_SB(b, h) + boff + n * 2048 + k * 1024); } while (0)
; #define PG8_MMA(ai, bj, At, Bt) do { __builtin_amdgcn_s_setprio(1); _Pragma("unroll") for (int m = 0; m < 4; ++m) _Pragma("unroll") for (int n = 0; n < 2; ++n) _Pragma("unroll") for (int k = 0; k < 2; ++k) \
;         acc[ai][bj][m][n] = __builtin_amdgcn_mfma_f32_16x16x32_bf16(Bt[n][k], At[m][k], acc[ai][bj][m][n], 0, 0, 0); __builtin_amdgcn_s_setprio(0); } while (0)
; #define PG8_WAIT_V(n) asm volatile("s_waitcnt vmcnt(" #n ")" ::: "memory")
; #define PG8_WAIT_L(n) asm volatile("s_waitcnt lgkmcnt(" #n ")" ::: "memory")
; template <class Epi, class Sched, bool ALIGN_EPI = false, bool SP2 = false>
; __device__ __forceinline__ void gemm_phase(PG8_LAS unsigned char* lds, const Gemm g, const Sched& S, const Epi& E) {
;     ...
;             const bool last = (t == nt - 2);
;             const char* a1 = cA + (size_t)(t + 1) * kstep;
;             const char* a2 = last ? nA : cA + (size_t)(t + 2) * kstep; const char* b2 = last ? nB : cB + (size_t)(t + 2) * kstep;
;             const char* a3 = a2 + kstep; const char* b3 = b2 + kstep;
;             if (last && has_next) S.a_ready(nxt);
;             if constexpr (SP2) {
;             PG8_LDB(B0, 0, 0); PG8_LDB(B1, 0, 1); PG8_SCHED; PG8_LDA(At, 0, 0); PG8_STAGE(PG8_SA(1, 1), a1 + hstep, voffA);
;             PG8_WAIT_V(8); PG8_WAIT_L(0); PG8_BAR; PG8_MMA(0, 0, At, B0); PG8_MMA(0, 1, At, B1); PG8_BAR; PG8_SCHED;
;             PG8_LDA(At, 0, 1); PG8_STAGE(PG8_SB(0, 0), b2, voffB); PG8_STAGE(PG8_SB(0, 1), b2 + hstep, voffB); PG8_STAGE(PG8_SA(0, 0), a2, voffA);
;             PG8_WAIT_V(8); PG8_WAIT_L(0); PG8_BAR; PG8_MMA(1, 0, At, B0); PG8_MMA(1, 1, At, B1); PG8_BAR; PG8_SCHED;
.LBB0_458:
	ds_read_b128 v[140:143], v149
	ds_read_b128 v[152:155], v149 offset:1024
	ds_read_b128 v[156:159], v149 offset:2048
	ds_read_b128 v[160:163], v149 offset:3072
	ds_read_b128 v[164:167], v150
	ds_read_b128 v[168:171], v150 offset:1024
	ds_read_b128 v[172:175], v150 offset:2048
	ds_read_b128 v[176:179], v150 offset:3072
	s_add_u32 s28, s26, 0xfff80080
	s_addc_u32 s29, s27, -1
	s_cmp_eq_u32 s49, 28
	s_cselect_b32 s35, s19, s29
	s_cselect_b32 s34, s31, s28
	s_cselect_b32 s29, s17, s48
	s_cselect_b32 s28, s46, s47
	v_lshl_add_u64 v[144:145], s[26:27], 0, v[132:133]
	s_add_i32 m0, s25, 0xc000
	ds_read_b128 v[180:183], v151
	ds_read_b128 v[184:187], v151 offset:1024
	ds_read_b128 v[188:191], v151 offset:2048
	ds_read_b128 v[192:195], v151 offset:3072
	ds_read_b128 v[196:199], v151 offset:4096
	ds_read_b128 v[200:203], v151 offset:5120
	ds_read_b128 v[204:207], v151 offset:6144
	ds_read_b128 v[208:211], v151 offset:7168
	global_load_lds_dwordx4 v[144:145], off
	v_lshl_add_u64 v[144:145], s[26:27], 0, v[134:135]
	s_add_i32 m0, s25, 0xe000
	s_nop 0
	global_load_lds_dwordx4 v[144:145], off
	s_waitcnt vmcnt(8)
	s_waitcnt lgkmcnt(0)
	s_barrier
	s_setprio 1
	s_waitcnt lgkmcnt(0)
	v_mfma_f32_16x16x32_bf16 v[124:127], v[140:143], v[180:183], v[124:127]
	v_mfma_f32_16x16x32_bf16 v[124:127], v[152:155], v[184:187], v[124:127]
	v_mfma_f32_16x16x32_bf16 v[120:123], v[156:159], v[180:183], v[120:123]
	v_mfma_f32_16x16x32_bf16 v[120:123], v[160:163], v[184:187], v[120:123]
	v_mfma_f32_16x16x32_bf16 v[116:119], v[140:143], v[188:191], v[116:119]
	v_mfma_f32_16x16x32_bf16 v[116:119], v[152:155], v[192:195], v[116:119]
	v_mfma_f32_16x16x32_bf16 v[112:115], v[156:159], v[188:191], v[112:115]
	v_mfma_f32_16x16x32_bf16 v[112:115], v[160:163], v[192:195], v[112:115]
	v_mfma_f32_16x16x32_bf16 v[108:111], v[140:143], v[196:199], v[108:111]
	v_mfma_f32_16x16x32_bf16 v[108:111], v[152:155], v[200:203], v[108:111]
	v_mfma_f32_16x16x32_bf16 v[100:103], v[156:159], v[196:199], v[100:103]
	v_mfma_f32_16x16x32_bf16 v[100:103], v[160:163], v[200:203], v[100:103]
	v_mfma_f32_16x16x32_bf16 v[92:95], v[140:143], v[204:207], v[92:95]
	v_mfma_f32_16x16x32_bf16 v[92:95], v[152:155], v[208:211], v[92:95]
	v_mfma_f32_16x16x32_bf16 v[80:83], v[156:159], v[204:207], v[80:83]
	v_mfma_f32_16x16x32_bf16 v[80:83], v[160:163], v[208:211], v[80:83]
	s_setprio 0
	s_setprio 1
	v_mfma_f32_16x16x32_bf16 v[104:107], v[164:167], v[180:183], v[104:107]
	v_mfma_f32_16x16x32_bf16 v[104:107], v[168:171], v[184:187], v[104:107]
	v_mfma_f32_16x16x32_bf16 v[96:99], v[172:175], v[180:183], v[96:99]
	v_mfma_f32_16x16x32_bf16 v[96:99], v[176:179], v[184:187], v[96:99]
	v_mfma_f32_16x16x32_bf16 v[88:91], v[164:167], v[188:191], v[88:91]
	v_mfma_f32_16x16x32_bf16 v[88:91], v[168:171], v[192:195], v[88:91]
	v_mfma_f32_16x16x32_bf16 v[84:87], v[172:175], v[188:191], v[84:87]
	v_mfma_f32_16x16x32_bf16 v[84:87], v[176:179], v[192:195], v[84:87]
	v_mfma_f32_16x16x32_bf16 v[76:79], v[164:167], v[196:199], v[76:79]
	v_mfma_f32_16x16x32_bf16 v[76:79], v[168:171], v[200:203], v[76:79]
	v_mfma_f32_16x16x32_bf16 v[72:75], v[172:175], v[196:199], v[72:75]
	v_mfma_f32_16x16x32_bf16 v[72:75], v[176:179], v[200:203], v[72:75]
	v_mfma_f32_16x16x32_bf16 v[68:71], v[164:167], v[204:207], v[68:71]
	v_mfma_f32_16x16x32_bf16 v[68:71], v[168:171], v[208:211], v[68:71]
	v_mfma_f32_16x16x32_bf16 v[64:67], v[172:175], v[204:207], v[64:67]
	v_mfma_f32_16x16x32_bf16 v[64:67], v[176:179], v[208:211], v[64:67]
	s_setprio 0
	s_barrier
	s_add_i32 s50, s43, s30
	v_lshl_add_u64 v[144:145], s[28:29], 0, v[128:129]
	s_mov_b32 m0, s50
	ds_read_b128 v[180:183], v151 offset:16384
	ds_read_b128 v[184:187], v151 offset:17408
	ds_read_b128 v[188:191], v151 offset:18432
	ds_read_b128 v[192:195], v151 offset:19456
	ds_read_b128 v[196:199], v151 offset:20480
	ds_read_b128 v[200:203], v151 offset:21504
	ds_read_b128 v[204:207], v151 offset:22528
	ds_read_b128 v[208:211], v151 offset:23552
	global_load_lds_dwordx4 v[144:145], off
	s_add_i32 m0, s50, 0x2000
	s_add_u32 s50, s28, 0x80000
	v_lshl_add_u64 v[212:213], s[28:29], 0, v[130:131]
	s_addc_u32 s51, s29, 0
	s_add_i32 s52, s44, s30
	global_load_lds_dwordx4 v[212:213], off
	v_lshl_add_u64 v[214:215], s[50:51], 0, v[128:129]
	s_mov_b32 m0, s52
	v_lshl_add_u64 v[216:217], s[34:35], 0, v[130:131]
	global_load_lds_dwordx4 v[214:215], off
	v_lshl_add_u64 v[214:215], s[50:51], 0, v[130:131]
	s_add_i32 m0, s52, 0x2000
	s_nop 0
	global_load_lds_dwordx4 v[214:215], off
	v_lshl_add_u64 v[214:215], s[34:35], 0, v[128:129]
	s_mov_b32 m0, s25
	s_nop 0
	global_load_lds_dwordx4 v[214:215], off
	s_mov_b32 m0, s36
	s_nop 0
	global_load_lds_dwordx4 v[216:217], off
	s_waitcnt vmcnt(8)
	s_waitcnt lgkmcnt(0)
	s_barrier
; #define PG8_STAGE(bufoff, gbase, voff) do { _Pragma("unroll") for (int _i = 0; _i < 2; ++_i) \
;         __builtin_amdgcn_global_load_lds((const unsigned*)((const char*)(gbase) + (voff)[_i]), (PG8_LAS unsigned*)(lds + (bufoff) + ldsw + _i * 8192), 16, 0, 0); } while (0)
; #define PG8_LDA(dst, b, h) do { _Pragma("unroll") for (int m = 0; m < 4; ++m) _Pragma("unroll") for (int k = 0; k < 2; ++k) dst[m][k] = *(const PG8_LAS bf16x8*)(lds + PG8_SA(b, h) + aoff + m * 2048 + k * 1024); } while (0)
; #define PG8_LDB(dst, b, h) do { _Pragma("unroll") for (int n = 0; n < 2; ++n) _Pragma("unroll") for (int k = 0; k < 2; ++k) dst[n][k] = *(const PG8_LAS bf16x8*)(lds + PG8_SB(b, h) + boff + n * 2048 + k * 1024); } while (0)
; #define PG8_MMA(ai, bj, At, Bt) do { __builtin_amdgcn_s_setprio(1); _Pragma("unroll") for (int m = 0; m < 4; ++m) _Pragma("unroll") for (int n = 0; n < 2; ++n) _Pragma("unroll") for (int k = 0; k < 2; ++k) \
;         acc[ai][bj][m][n] = __builtin_amdgcn_mfma_f32_16x16x32_bf16(Bt[n][k], At[m][k], acc[ai][bj][m][n], 0, 0, 0); __builtin_amdgcn_s_setprio(0); } while (0)
; #define PG8_WAIT_V(n) asm volatile("s_waitcnt vmcnt(" #n ")" ::: "memory")
; #define PG8_WAIT_L(n) asm volatile("s_waitcnt lgkmcnt(" #n ")" ::: "memory")
; #define PG8_BAR __builtin_amdgcn_s_barrier()
; #define PG8_SCHED __builtin_amdgcn_sched_barrier(0)
; template <class Epi, class Sched, bool ALIGN_EPI = false, bool SP2 = false>
; __device__ __forceinline__ void gemm_phase(PG8_LAS unsigned char* lds, const Gemm g, const Sched& S, const Epi& E) {
;     ...
;             PG8_WAIT_V(8); PG8_WAIT_L(0); PG8_BAR; PG8_MMA(1, 0, At, B0); PG8_MMA(1, 1, At, B1); PG8_BAR; PG8_SCHED;
;             PG8_LDB(B0, 1, 0); PG8_LDB(B1, 1, 1); PG8_SCHED; PG8_LDA(At, 1, 0); PG8_STAGE(PG8_SA(0, 1), a2 + hstep, voffA);
;             PG8_WAIT_V(8); PG8_WAIT_L(0); PG8_BAR; PG8_MMA(0, 0, At, B0); PG8_MMA(0, 1, At, B1); PG8_BAR; PG8_SCHED;
	s_setprio 1
	s_waitcnt lgkmcnt(0)
	v_mfma_f32_16x16x32_bf16 v[60:63], v[140:143], v[180:183], v[60:63]
	v_mfma_f32_16x16x32_bf16 v[60:63], v[152:155], v[184:187], v[60:63]
	v_mfma_f32_16x16x32_bf16 v[56:59], v[156:159], v[180:183], v[56:59]
	v_mfma_f32_16x16x32_bf16 v[56:59], v[160:163], v[184:187], v[56:59]
	v_mfma_f32_16x16x32_bf16 v[52:55], v[140:143], v[188:191], v[52:55]
	v_mfma_f32_16x16x32_bf16 v[52:55], v[152:155], v[192:195], v[52:55]
	v_mfma_f32_16x16x32_bf16 v[48:51], v[156:159], v[188:191], v[48:51]
	v_mfma_f32_16x16x32_bf16 v[48:51], v[160:163], v[192:195], v[48:51]
	v_mfma_f32_16x16x32_bf16 v[44:47], v[140:143], v[196:199], v[44:47]
	v_mfma_f32_16x16x32_bf16 v[44:47], v[152:155], v[200:203], v[44:47]
	v_mfma_f32_16x16x32_bf16 v[36:39], v[156:159], v[196:199], v[36:39]
	v_mfma_f32_16x16x32_bf16 v[36:39], v[160:163], v[200:203], v[36:39]
	v_mfma_f32_16x16x32_bf16 v[28:31], v[140:143], v[204:207], v[28:31]
	v_mfma_f32_16x16x32_bf16 v[28:31], v[152:155], v[208:211], v[28:31]
	v_mfma_f32_16x16x32_bf16 v[16:19], v[156:159], v[204:207], v[16:19]
	v_mfma_f32_16x16x32_bf16 v[16:19], v[160:163], v[208:211], v[16:19]
	s_setprio 0
	s_setprio 1
	v_mfma_f32_16x16x32_bf16 v[40:43], v[164:167], v[180:183], v[40:43]
	v_mfma_f32_16x16x32_bf16 v[40:43], v[168:171], v[184:187], v[40:43]
	v_mfma_f32_16x16x32_bf16 v[32:35], v[172:175], v[180:183], v[32:35]
	v_mfma_f32_16x16x32_bf16 v[32:35], v[176:179], v[184:187], v[32:35]
	v_mfma_f32_16x16x32_bf16 v[24:27], v[164:167], v[188:191], v[24:27]
	v_mfma_f32_16x16x32_bf16 v[24:27], v[168:171], v[192:195], v[24:27]
	v_mfma_f32_16x16x32_bf16 v[20:23], v[172:175], v[188:191], v[20:23]
	v_mfma_f32_16x16x32_bf16 v[20:23], v[176:179], v[192:195], v[20:23]
	v_mfma_f32_16x16x32_bf16 v[12:15], v[164:167], v[196:199], v[12:15]
	v_mfma_f32_16x16x32_bf16 v[12:15], v[168:171], v[200:203], v[12:15]
	v_mfma_f32_16x16x32_bf16 v[8:11], v[172:175], v[196:199], v[8:11]
	v_mfma_f32_16x16x32_bf16 v[8:11], v[176:179], v[200:203], v[8:11]
	v_mfma_f32_16x16x32_bf16 v[4:7], v[164:167], v[204:207], v[4:7]
	v_mfma_f32_16x16x32_bf16 v[4:7], v[168:171], v[208:211], v[4:7]
	v_mfma_f32_16x16x32_bf16 v[0:3], v[172:175], v[204:207], v[0:3]
	v_mfma_f32_16x16x32_bf16 v[0:3], v[176:179], v[208:211], v[0:3]
	s_setprio 0
	s_barrier
	s_add_i32 s50, 0, 0x18000
	s_add_i32 s51, 0, 0x1c000
	v_add_u32_e32 v160, s50, v147
	v_add_u32_e32 v176, s51, v147
	ds_read_b128 v[140:143], v160
	ds_read_b128 v[152:155], v160 offset:1024
	ds_read_b128 v[156:159], v160 offset:2048
	ds_read_b128 v[160:163], v160 offset:3072
	ds_read_b128 v[164:167], v176
	ds_read_b128 v[168:171], v176 offset:1024
	ds_read_b128 v[172:175], v176 offset:2048
	ds_read_b128 v[176:179], v176 offset:3072
	s_add_u32 s34, s34, 0x80000
	s_addc_u32 s35, s35, 0
	s_mov_b32 m0, s37
	v_lshl_add_u64 v[218:219], s[34:35], 0, v[128:129]
	ds_read_b128 v[180:183], v151 offset:32768
	ds_read_b128 v[184:187], v151 offset:33792
	ds_read_b128 v[188:191], v151 offset:34816
	ds_read_b128 v[192:195], v151 offset:35840
	ds_read_b128 v[196:199], v151 offset:36864
	ds_read_b128 v[200:203], v151 offset:37888
	ds_read_b128 v[204:207], v151 offset:38912
	ds_read_b128 v[208:211], v151 offset:39936
	global_load_lds_dwordx4 v[218:219], off
	v_lshl_add_u64 v[218:219], s[34:35], 0, v[130:131]
	s_mov_b32 m0, s38
	s_nop 0
	global_load_lds_dwordx4 v[218:219], off
	s_waitcnt vmcnt(8)
	s_waitcnt lgkmcnt(0)
	s_barrier
	s_setprio 1
	s_waitcnt lgkmcnt(0)
	v_mfma_f32_16x16x32_bf16 v[124:127], v[140:143], v[180:183], v[124:127]
	v_mfma_f32_16x16x32_bf16 v[124:127], v[152:155], v[184:187], v[124:127]
	v_mfma_f32_16x16x32_bf16 v[120:123], v[156:159], v[180:183], v[120:123]
	v_mfma_f32_16x16x32_bf16 v[120:123], v[160:163], v[184:187], v[120:123]
	v_mfma_f32_16x16x32_bf16 v[116:119], v[140:143], v[188:191], v[116:119]
	v_mfma_f32_16x16x32_bf16 v[116:119], v[152:155], v[192:195], v[116:119]
	v_mfma_f32_16x16x32_bf16 v[112:115], v[156:159], v[188:191], v[112:115]
	v_mfma_f32_16x16x32_bf16 v[112:115], v[160:163], v[192:195], v[112:115]
	v_mfma_f32_16x16x32_bf16 v[108:111], v[140:143], v[196:199], v[108:111]
	v_mfma_f32_16x16x32_bf16 v[108:111], v[152:155], v[200:203], v[108:111]
	v_mfma_f32_16x16x32_bf16 v[100:103], v[156:159], v[196:199], v[100:103]
	v_mfma_f32_16x16x32_bf16 v[100:103], v[160:163], v[200:203], v[100:103]
	v_mfma_f32_16x16x32_bf16 v[92:95], v[140:143], v[204:207], v[92:95]
	v_mfma_f32_16x16x32_bf16 v[92:95], v[152:155], v[208:211], v[92:95]
	v_mfma_f32_16x16x32_bf16 v[80:83], v[156:159], v[204:207], v[80:83]
	v_mfma_f32_16x16x32_bf16 v[80:83], v[160:163], v[208:211], v[80:83]
	s_setprio 0
	s_setprio 1
	v_mfma_f32_16x16x32_bf16 v[104:107], v[164:167], v[180:183], v[104:107]
	v_mfma_f32_16x16x32_bf16 v[104:107], v[168:171], v[184:187], v[104:107]
	v_mfma_f32_16x16x32_bf16 v[96:99], v[172:175], v[180:183], v[96:99]
	v_mfma_f32_16x16x32_bf16 v[96:99], v[176:179], v[184:187], v[96:99]
	v_mfma_f32_16x16x32_bf16 v[88:91], v[164:167], v[188:191], v[88:91]
	v_mfma_f32_16x16x32_bf16 v[88:91], v[168:171], v[192:195], v[88:91]
	v_mfma_f32_16x16x32_bf16 v[84:87], v[172:175], v[188:191], v[84:87]
	v_mfma_f32_16x16x32_bf16 v[84:87], v[176:179], v[192:195], v[84:87]
	v_mfma_f32_16x16x32_bf16 v[76:79], v[164:167], v[196:199], v[76:79]
	v_mfma_f32_16x16x32_bf16 v[76:79], v[168:171], v[200:203], v[76:79]
	v_mfma_f32_16x16x32_bf16 v[72:75], v[172:175], v[196:199], v[72:75]
	v_mfma_f32_16x16x32_bf16 v[72:75], v[176:179], v[200:203], v[72:75]
	v_mfma_f32_16x16x32_bf16 v[68:71], v[164:167], v[204:207], v[68:71]
	v_mfma_f32_16x16x32_bf16 v[68:71], v[168:171], v[208:211], v[68:71]
	v_mfma_f32_16x16x32_bf16 v[64:67], v[172:175], v[204:207], v[64:67]
	v_mfma_f32_16x16x32_bf16 v[64:67], v[176:179], v[208:211], v[64:67]
	s_setprio 0
	s_barrier
; #define PG8_STAGE(bufoff, gbase, voff) do { _Pragma("unroll") for (int _i = 0; _i < 2; ++_i) \
;         __builtin_amdgcn_global_load_lds((const unsigned*)((const char*)(gbase) + (voff)[_i]), (PG8_LAS unsigned*)(lds + (bufoff) + ldsw + _i * 8192), 16, 0, 0); } while (0)
; #define PG8_LDA(dst, b, h) do { _Pragma("unroll") for (int m = 0; m < 4; ++m) _Pragma("unroll") for (int k = 0; k < 2; ++k) dst[m][k] = *(const PG8_LAS bf16x8*)(lds + PG8_SA(b, h) + aoff + m * 2048 + k * 1024); } while (0)
; #define PG8_MMA(ai, bj, At, Bt) do { __builtin_amdgcn_s_setprio(1); _Pragma("unroll") for (int m = 0; m < 4; ++m) _Pragma("unroll") for (int n = 0; n < 2; ++n) _Pragma("unroll") for (int k = 0; k < 2; ++k) \
;         acc[ai][bj][m][n] = __builtin_amdgcn_mfma_f32_16x16x32_bf16(Bt[n][k], At[m][k], acc[ai][bj][m][n], 0, 0, 0); __builtin_amdgcn_s_setprio(0); } while (0)
; #define PG8_WAIT_V(n) asm volatile("s_waitcnt vmcnt(" #n ")" ::: "memory")
; #define PG8_WAIT_L(n) asm volatile("s_waitcnt lgkmcnt(" #n ")" ::: "memory")
; #define PG8_BAR __builtin_amdgcn_s_barrier()
; #define PG8_SCHED __builtin_amdgcn_sched_barrier(0)
; template <class Epi, class Sched, bool ALIGN_EPI = false, bool SP2 = false>
; __device__ __forceinline__ void gemm_phase(PG8_LAS unsigned char* lds, const Gemm g, const Sched& S, const Epi& E) {
;     ...
;         for (int t = 0; t < nt; t += 2) {
;     ...
;             PG8_LDA(At, 1, 1); PG8_STAGE(PG8_SB(1, 0), b3, voffB); PG8_STAGE(PG8_SB(1, 1), b3 + hstep, voffB); PG8_STAGE(PG8_SA(1, 0), a3, voffA);
;             PG8_WAIT_V(8); PG8_WAIT_L(0); PG8_BAR; PG8_MMA(1, 0, At, B0); PG8_MMA(1, 1, At, B1); PG8_BAR; PG8_SCHED;
	s_add_i32 s34, s50, s30
	v_lshl_add_u64 v[144:145], v[144:145], 0, s[4:5]
	s_mov_b32 m0, s34
	ds_read_b128 v[180:183], v151 offset:49152
	ds_read_b128 v[184:187], v151 offset:50176
	ds_read_b128 v[188:191], v151 offset:51200
	ds_read_b128 v[192:195], v151 offset:52224
	ds_read_b128 v[196:199], v151 offset:53248
	ds_read_b128 v[200:203], v151 offset:54272
	ds_read_b128 v[204:207], v151 offset:55296
	ds_read_b128 v[208:211], v151 offset:56320
	global_load_lds_dwordx4 v[144:145], off
	s_add_i32 m0, s34, 0x2000
	s_add_u32 s28, s28, 0x80080
	v_lshl_add_u64 v[144:145], v[212:213], 0, s[4:5]
	s_addc_u32 s29, s29, 0
	s_add_i32 s34, s51, s30
	global_load_lds_dwordx4 v[144:145], off
	v_lshl_add_u64 v[144:145], s[28:29], 0, v[128:129]
	s_mov_b32 m0, s34
	s_nop 0
	global_load_lds_dwordx4 v[144:145], off
	v_lshl_add_u64 v[144:145], s[28:29], 0, v[130:131]
	s_add_i32 m0, s34, 0x2000
	s_nop 0
	global_load_lds_dwordx4 v[144:145], off
	v_lshl_add_u64 v[144:145], v[214:215], 0, s[4:5]
	s_mov_b32 m0, s41
	s_nop 0
	global_load_lds_dwordx4 v[144:145], off
	v_lshl_add_u64 v[144:145], v[216:217], 0, s[4:5]
	s_mov_b32 m0, s42
	s_nop 0
	global_load_lds_dwordx4 v[144:145], off
	s_waitcnt vmcnt(8)
	s_waitcnt lgkmcnt(0)
	s_barrier
	s_setprio 1
	s_waitcnt lgkmcnt(0)
	v_mfma_f32_16x16x32_bf16 v[60:63], v[140:143], v[180:183], v[60:63]
	v_mfma_f32_16x16x32_bf16 v[60:63], v[152:155], v[184:187], v[60:63]
	v_mfma_f32_16x16x32_bf16 v[56:59], v[156:159], v[180:183], v[56:59]
	v_mfma_f32_16x16x32_bf16 v[56:59], v[160:163], v[184:187], v[56:59]
	v_mfma_f32_16x16x32_bf16 v[52:55], v[140:143], v[188:191], v[52:55]
	v_mfma_f32_16x16x32_bf16 v[52:55], v[152:155], v[192:195], v[52:55]
	v_mfma_f32_16x16x32_bf16 v[48:51], v[156:159], v[188:191], v[48:51]
	v_mfma_f32_16x16x32_bf16 v[48:51], v[160:163], v[192:195], v[48:51]
	v_mfma_f32_16x16x32_bf16 v[44:47], v[140:143], v[196:199], v[44:47]
	v_mfma_f32_16x16x32_bf16 v[44:47], v[152:155], v[200:203], v[44:47]
	v_mfma_f32_16x16x32_bf16 v[36:39], v[156:159], v[196:199], v[36:39]
	v_mfma_f32_16x16x32_bf16 v[36:39], v[160:163], v[200:203], v[36:39]
	v_mfma_f32_16x16x32_bf16 v[28:31], v[140:143], v[204:207], v[28:31]
	v_mfma_f32_16x16x32_bf16 v[28:31], v[152:155], v[208:211], v[28:31]
	v_mfma_f32_16x16x32_bf16 v[16:19], v[156:159], v[204:207], v[16:19]
	v_mfma_f32_16x16x32_bf16 v[16:19], v[160:163], v[208:211], v[16:19]
	s_setprio 0
	s_setprio 1
	v_mfma_f32_16x16x32_bf16 v[40:43], v[164:167], v[180:183], v[40:43]
	v_mfma_f32_16x16x32_bf16 v[40:43], v[168:171], v[184:187], v[40:43]
	v_mfma_f32_16x16x32_bf16 v[32:35], v[172:175], v[180:183], v[32:35]
	v_mfma_f32_16x16x32_bf16 v[32:35], v[176:179], v[184:187], v[32:35]
	v_mfma_f32_16x16x32_bf16 v[24:27], v[164:167], v[188:191], v[24:27]
	v_mfma_f32_16x16x32_bf16 v[24:27], v[168:171], v[192:195], v[24:27]
	v_mfma_f32_16x16x32_bf16 v[20:23], v[172:175], v[188:191], v[20:23]
	v_mfma_f32_16x16x32_bf16 v[20:23], v[176:179], v[192:195], v[20:23]
	v_mfma_f32_16x16x32_bf16 v[12:15], v[164:167], v[196:199], v[12:15]
	v_mfma_f32_16x16x32_bf16 v[12:15], v[168:171], v[200:203], v[12:15]
	v_mfma_f32_16x16x32_bf16 v[8:11], v[172:175], v[196:199], v[8:11]
	v_mfma_f32_16x16x32_bf16 v[8:11], v[176:179], v[200:203], v[8:11]
	v_mfma_f32_16x16x32_bf16 v[4:7], v[164:167], v[204:207], v[4:7]
	v_mfma_f32_16x16x32_bf16 v[4:7], v[168:171], v[208:211], v[4:7]
	v_mfma_f32_16x16x32_bf16 v[0:3], v[172:175], v[204:207], v[0:3]
	v_mfma_f32_16x16x32_bf16 v[0:3], v[176:179], v[208:211], v[0:3]
	s_setprio 0
	s_barrier
	s_add_i32 s49, s49, 2
	s_add_u32 s26, s26, 0x100
	s_addc_u32 s27, s27, 0
	s_add_u32 s47, s47, 0x100
	s_addc_u32 s48, s48, 0
	s_cmp_gt_u32 s49, 29
	s_cbranch_scc0 .LBB0_458
	s_and_b64 vcc, exec, s[6:7]
	s_cbranch_vccz .LBB0_461
	s_barrier
